# dense attention loops: priority reset to 0 at loop exit so item epilogue/prologue no longer pre-empt the co-resident wave's MFMA phases
# speedup vs baseline: 1.0392x; 1.0094x over previous
; DI unsigned pk2(float a, float b) { f32x2 v = {a, b}; bf16x2_t r = __builtin_convertvector(v, bf16x2_t); return __builtin_bit_cast(unsigned, r); }
; template <int DQK, bool BAND, int QT> ...
;     ...
;         const float mc = -m[qt] * cc;
;         float ls = 0.f;
; #pragma unroll
;         for (int a = 0; a < 2; ++a) {
; #pragma unroll
;           for (int r = 0; r < 16; ++r) { const float pv = __builtin_amdgcn_exp2f(fmaf(s[a][qt][r], cc, mc)); s[a][qt][r] = pv; ls += pv; }
; #pragma unroll
;           for (int s2 = 0; s2 < 2; ++s2) {
;             u32x4 pk;
;             pk.x = pk2(s[a][qt][8 * s2 + 0], s[a][qt][8 * s2 + 1]);
;             pk.y = pk2(s[a][qt][8 * s2 + 2], s[a][qt][8 * s2 + 3]);
;             pk.z = pk2(s[a][qt][8 * s2 + 4], s[a][qt][8 * s2 + 5]);
;             pk.w = pk2(s[a][qt][8 * s2 + 6], s[a][qt][8 * s2 + 7]);
;             pf[qt][a * 2 + s2] = __builtin_bit_cast(bf16x8, pk);
;           }
;         }
;         l[qt] += ls;
;       }
;       __builtin_amdgcn_s_setprio(0);
;       if (more) lstore(lds + ((it + 1) & 1) * ST);
; #pragma unroll
;       for (int ks = 0; ks < 4; ++ks) {
;         const bf16x8 v0 = *(const bf16x8*)(st + v_rd + ks * 32);
;         const bf16x8 v1 = *(const bf16x8*)(st + v_rd + 32 * LROW + ks * 32);
.Lgqa_nostage:
	v_mul_f32_e32 v254, 0xbe38aa3b, v197
	v_mul_f32_e32 v255, 0xbe38aa3b, v202
	v_fmamk_f32 v82, v82, 0x3e38aa3b, v254
	v_fmamk_f32 v114, v114, 0x3e38aa3b, v255
	v_fmamk_f32 v83, v83, 0x3e38aa3b, v254
	v_fmamk_f32 v115, v115, 0x3e38aa3b, v255
	v_fmamk_f32 v84, v84, 0x3e38aa3b, v254
	v_fmamk_f32 v116, v116, 0x3e38aa3b, v255
	v_fmamk_f32 v85, v85, 0x3e38aa3b, v254
	v_fmamk_f32 v117, v117, 0x3e38aa3b, v255
	v_fmamk_f32 v86, v86, 0x3e38aa3b, v254
	v_fmamk_f32 v118, v118, 0x3e38aa3b, v255
	v_fmamk_f32 v87, v87, 0x3e38aa3b, v254
	v_fmamk_f32 v119, v119, 0x3e38aa3b, v255
	v_fmamk_f32 v88, v88, 0x3e38aa3b, v254
	v_fmamk_f32 v120, v120, 0x3e38aa3b, v255
	v_fmamk_f32 v89, v89, 0x3e38aa3b, v254
	v_fmamk_f32 v121, v121, 0x3e38aa3b, v255
	v_exp_f32_e32 v82, v82
	v_exp_f32_e32 v114, v114
	v_exp_f32_e32 v83, v83
	v_exp_f32_e32 v115, v115
	v_exp_f32_e32 v84, v84
	v_exp_f32_e32 v116, v116
	v_exp_f32_e32 v85, v85
	v_exp_f32_e32 v117, v117
	v_exp_f32_e32 v86, v86
	v_exp_f32_e32 v118, v118
	v_exp_f32_e32 v87, v87
	v_exp_f32_e32 v119, v119
	v_exp_f32_e32 v88, v88
	v_exp_f32_e32 v120, v120
	v_exp_f32_e32 v89, v89
	v_exp_f32_e32 v121, v121
	v_fmamk_f32 v90, v90, 0x3e38aa3b, v254
	v_fmamk_f32 v122, v122, 0x3e38aa3b, v255
	v_fmamk_f32 v91, v91, 0x3e38aa3b, v254
	v_fmamk_f32 v123, v123, 0x3e38aa3b, v255
	v_fmamk_f32 v92, v92, 0x3e38aa3b, v254
	v_fmamk_f32 v124, v124, 0x3e38aa3b, v255
	v_fmamk_f32 v93, v93, 0x3e38aa3b, v254
	v_fmamk_f32 v125, v125, 0x3e38aa3b, v255
	v_fmamk_f32 v94, v94, 0x3e38aa3b, v254
	v_fmamk_f32 v126, v126, 0x3e38aa3b, v255
	v_fmamk_f32 v95, v95, 0x3e38aa3b, v254
	v_fmamk_f32 v127, v127, 0x3e38aa3b, v255
	v_fmamk_f32 v96, v96, 0x3e38aa3b, v254
	v_fmamk_f32 v128, v128, 0x3e38aa3b, v255
	v_fmamk_f32 v97, v97, 0x3e38aa3b, v254
	v_fmamk_f32 v129, v129, 0x3e38aa3b, v255
	v_exp_f32_e32 v90, v90
	v_exp_f32_e32 v122, v122
	v_exp_f32_e32 v91, v91
	v_exp_f32_e32 v123, v123
	v_exp_f32_e32 v92, v92
	v_exp_f32_e32 v124, v124
	v_exp_f32_e32 v93, v93
	v_exp_f32_e32 v125, v125
	v_exp_f32_e32 v94, v94
	v_exp_f32_e32 v126, v126
	v_exp_f32_e32 v95, v95
	v_exp_f32_e32 v127, v127
	v_exp_f32_e32 v96, v96
	v_exp_f32_e32 v128, v128
	v_exp_f32_e32 v97, v97
	v_exp_f32_e32 v129, v129
	v_cvt_pk_bf16_f32 v82, v82, v83
	v_cvt_pk_bf16_f32 v114, v114, v115
	v_cvt_pk_bf16_f32 v83, v84, v85
	v_cvt_pk_bf16_f32 v115, v116, v117
	v_cvt_pk_bf16_f32 v84, v86, v87
	v_cvt_pk_bf16_f32 v116, v118, v119
	v_cvt_pk_bf16_f32 v85, v88, v89
	v_cvt_pk_bf16_f32 v117, v120, v121
	v_fmamk_f32 v66, v66, 0x3e38aa3b, v254
	v_fmamk_f32 v98, v98, 0x3e38aa3b, v255
	v_fmamk_f32 v67, v67, 0x3e38aa3b, v254
	v_fmamk_f32 v99, v99, 0x3e38aa3b, v255
	v_fmamk_f32 v68, v68, 0x3e38aa3b, v254
	v_fmamk_f32 v100, v100, 0x3e38aa3b, v255
	v_fmamk_f32 v69, v69, 0x3e38aa3b, v254
	v_fmamk_f32 v101, v101, 0x3e38aa3b, v255
	v_fmamk_f32 v70, v70, 0x3e38aa3b, v254
	v_fmamk_f32 v102, v102, 0x3e38aa3b, v255
	v_fmamk_f32 v71, v71, 0x3e38aa3b, v254
	v_fmamk_f32 v103, v103, 0x3e38aa3b, v255
	v_fmamk_f32 v72, v72, 0x3e38aa3b, v254
	v_fmamk_f32 v104, v104, 0x3e38aa3b, v255
	v_fmamk_f32 v73, v73, 0x3e38aa3b, v254
	v_fmamk_f32 v105, v105, 0x3e38aa3b, v255
	v_exp_f32_e32 v66, v66
	v_exp_f32_e32 v98, v98
	v_exp_f32_e32 v67, v67
	v_exp_f32_e32 v99, v99
	v_exp_f32_e32 v68, v68
	v_exp_f32_e32 v100, v100
	v_exp_f32_e32 v69, v69
	v_exp_f32_e32 v101, v101
	v_exp_f32_e32 v70, v70
	v_exp_f32_e32 v102, v102
	v_exp_f32_e32 v71, v71
	v_exp_f32_e32 v103, v103
	v_exp_f32_e32 v72, v72
	v_exp_f32_e32 v104, v104
	v_exp_f32_e32 v73, v73
	v_exp_f32_e32 v105, v105
	v_cvt_pk_bf16_f32 v90, v90, v91
	v_cvt_pk_bf16_f32 v122, v122, v123
	v_cvt_pk_bf16_f32 v91, v92, v93
	v_cvt_pk_bf16_f32 v123, v124, v125
	v_cvt_pk_bf16_f32 v92, v94, v95
	v_cvt_pk_bf16_f32 v124, v126, v127
	v_cvt_pk_bf16_f32 v93, v96, v97
	v_cvt_pk_bf16_f32 v125, v128, v129
	v_fmamk_f32 v74, v74, 0x3e38aa3b, v254
	v_fmamk_f32 v106, v106, 0x3e38aa3b, v255
	v_fmamk_f32 v75, v75, 0x3e38aa3b, v254
	v_fmamk_f32 v107, v107, 0x3e38aa3b, v255
	v_fmamk_f32 v76, v76, 0x3e38aa3b, v254
	v_fmamk_f32 v108, v108, 0x3e38aa3b, v255
	v_fmamk_f32 v77, v77, 0x3e38aa3b, v254
	v_fmamk_f32 v109, v109, 0x3e38aa3b, v255
	v_fmamk_f32 v78, v78, 0x3e38aa3b, v254
	v_fmamk_f32 v110, v110, 0x3e38aa3b, v255
	v_fmamk_f32 v79, v79, 0x3e38aa3b, v254
	v_fmamk_f32 v111, v111, 0x3e38aa3b, v255
	v_fmamk_f32 v80, v80, 0x3e38aa3b, v254
	v_fmamk_f32 v112, v112, 0x3e38aa3b, v255
	v_fmamk_f32 v81, v81, 0x3e38aa3b, v254
	v_fmamk_f32 v113, v113, 0x3e38aa3b, v255
	v_exp_f32_e32 v74, v74
	v_exp_f32_e32 v106, v106
	v_exp_f32_e32 v75, v75
	v_exp_f32_e32 v107, v107
	v_exp_f32_e32 v76, v76
	v_exp_f32_e32 v108, v108
	v_exp_f32_e32 v77, v77
	v_exp_f32_e32 v109, v109
	v_exp_f32_e32 v78, v78
	v_exp_f32_e32 v110, v110
	v_exp_f32_e32 v79, v79
	v_exp_f32_e32 v111, v111
	v_exp_f32_e32 v80, v80
	v_exp_f32_e32 v112, v112
	v_exp_f32_e32 v81, v81
	v_exp_f32_e32 v113, v113
	v_cvt_pk_bf16_f32 v66, v66, v67
	v_cvt_pk_bf16_f32 v98, v98, v99
	v_cvt_pk_bf16_f32 v67, v68, v69
	v_cvt_pk_bf16_f32 v99, v100, v101
	v_cvt_pk_bf16_f32 v68, v70, v71
	v_cvt_pk_bf16_f32 v100, v102, v103
	v_cvt_pk_bf16_f32 v69, v72, v73
	v_cvt_pk_bf16_f32 v101, v104, v105
	v_cvt_pk_bf16_f32 v74, v74, v75
	v_cvt_pk_bf16_f32 v106, v106, v107
	v_cvt_pk_bf16_f32 v75, v76, v77
	v_cvt_pk_bf16_f32 v107, v108, v109
	v_cvt_pk_bf16_f32 v76, v78, v79
	v_cvt_pk_bf16_f32 v108, v110, v111
	v_cvt_pk_bf16_f32 v77, v80, v81
	v_cvt_pk_bf16_f32 v109, v112, v113
	s_setprio 2
	ds_read_b128 v[86:89], v183 offset:9216
	ds_read_b128 v[94:97], v183 offset:13824
	ds_read_b128 v[70:73], v183 offset:9248
	ds_read_b128 v[78:81], v183 offset:13856
	ds_read_b128 v[118:121], v183 offset:9280
	ds_read_b128 v[126:129], v183 offset:13888
	ds_read_b128 v[102:105], v183 offset:9312
	ds_read_b128 v[110:113], v183 offset:13920
	s_waitcnt lgkmcnt(7)
; #define MFMA(a, b, c) __builtin_amdgcn_mfma_f32_32x32x16_bf16((a), (b), (c), 0, 0, 0)
; template <int DQK, bool BAND, int QT> ...
;     ...
; #pragma unroll
;       for (int ks = 0; ks < 4; ++ks) {
;         const bf16x8 v0 = *(const bf16x8*)(st + v_rd + ks * 32);
;         const bf16x8 v1 = *(const bf16x8*)(st + v_rd + 32 * LROW + ks * 32);
; #pragma unroll
;         for (int qt = 0; qt < QT; ++qt) {
;           o[0][qt] = MFMA(v0, pf[qt][ks], o[0][qt]);
;           o[1][qt] = MFMA(v1, pf[qt][ks], o[1][qt]);
;         }
;       }
;     } else {
;       if (more) lstore(lds + ((it + 1) & 1) * ST);
;     }
;     __syncthreads();
;   }
; #pragma unroll
;   for (int qt = 0; qt < QT; ++qt) {
;     const float lt = l[qt] + __shfl_xor(l[qt], 32);
	v_mfma_f32_32x32x16_bf16 v[50:65], v[86:89], v[82:85], v[50:65]
	v_mfma_f32_32x32x16_bf16 v[18:33], v[86:89], v[114:117], v[18:33]
	s_waitcnt lgkmcnt(6)
	v_mfma_f32_32x32x16_bf16 v[34:49], v[94:97], v[82:85], v[34:49]
	v_mfma_f32_32x32x16_bf16 v[2:17], v[94:97], v[114:117], v[2:17]
	v_mfma_f32_16x16x32_bf16 v[240:243], v[244:247], v[82:85], v[240:243]
	v_mfma_f32_16x16x32_bf16 v[236:239], v[244:247], v[114:117], v[236:239]
	v_lshl_add_u64 v[192:193], v[192:193], 0, s[88:89]
	v_lshl_add_u64 v[194:195], v[194:195], 0, s[88:89]
	v_lshl_add_u64 v[188:189], v[188:189], 0, s[76:77]
	v_lshl_add_u64 v[190:191], v[190:191], 0, s[76:77]
	s_waitcnt lgkmcnt(5)
	v_mfma_f32_32x32x16_bf16 v[50:65], v[70:73], v[90:93], v[50:65]
	v_mfma_f32_32x32x16_bf16 v[18:33], v[70:73], v[122:125], v[18:33]
	s_waitcnt lgkmcnt(4)
	v_mfma_f32_32x32x16_bf16 v[34:49], v[78:81], v[90:93], v[34:49]
	v_mfma_f32_32x32x16_bf16 v[2:17], v[78:81], v[122:125], v[2:17]
	v_mfma_f32_16x16x32_bf16 v[240:243], v[244:247], v[90:93], v[240:243]
	v_mfma_f32_16x16x32_bf16 v[236:239], v[244:247], v[122:125], v[236:239]
	s_waitcnt lgkmcnt(3)
	v_mfma_f32_32x32x16_bf16 v[50:65], v[118:121], v[66:69], v[50:65]
	v_mfma_f32_32x32x16_bf16 v[18:33], v[118:121], v[98:101], v[18:33]
	s_waitcnt lgkmcnt(2)
	v_mfma_f32_32x32x16_bf16 v[34:49], v[126:129], v[66:69], v[34:49]
	v_mfma_f32_32x32x16_bf16 v[2:17], v[126:129], v[98:101], v[2:17]
	v_mfma_f32_16x16x32_bf16 v[240:243], v[244:247], v[66:69], v[240:243]
	v_mfma_f32_16x16x32_bf16 v[236:239], v[244:247], v[98:101], v[236:239]
	s_bitcmp1_b32 s1, 0
	s_cselect_b32 s7, -1, 1
	s_mulk_i32 s7, 0x4800
	v_add_u32_e32 v185, s7, v185
	v_add_u32_e32 v183, s7, v183
	s_add_i32 s1, s1, 1
	s_add_i32 s6, s6, 64
	s_waitcnt lgkmcnt(0)
	s_barrier
	v_mfma_f32_32x32x16_bf16 v[50:65], v[102:105], v[74:77], v[50:65]
	v_mfma_f32_32x32x16_bf16 v[18:33], v[102:105], v[106:109], v[18:33]
	v_mfma_f32_32x32x16_bf16 v[34:49], v[110:113], v[74:77], v[34:49]
	v_mfma_f32_32x32x16_bf16 v[2:17], v[110:113], v[106:109], v[2:17]
	v_mfma_f32_16x16x32_bf16 v[240:243], v[244:247], v[74:77], v[240:243]
	v_mfma_f32_16x16x32_bf16 v[236:239], v[244:247], v[106:109], v[236:239]
	s_cmp_lg_u32 s21, s1
	s_cbranch_scc1 .Lgqa_top
	s_setprio 0
	s_nop 7
	v_mbcnt_lo_u32_b32 v254, -1, 0
	v_mbcnt_hi_u32_b32 v254, -1, v254
	v_and_b32_e32 v255, 15, v254
	v_lshlrev_b32_e32 v255, 2, v255
	ds_bpermute_b32 v203, v255, v240
	ds_bpermute_b32 v253, v255, v241
	s_waitcnt lgkmcnt(0)
	v_cmp_gt_u32_e32 vcc, 16, v254
	s_nop 1
	v_cndmask_b32_e32 v187, v253, v203, vcc
	v_cmp_gt_u32_e32 vcc, 32, v254
	s_nop 1
	v_cndmask_b32_e32 v187, 0, v187, vcc
	ds_bpermute_b32 v203, v255, v236
	ds_bpermute_b32 v253, v255, v237
	s_waitcnt lgkmcnt(0)
	v_cmp_gt_u32_e32 vcc, 16, v254
	s_nop 1
	v_cndmask_b32_e32 v181, v253, v203, vcc
	v_cmp_gt_u32_e32 vcc, 32, v254
	s_nop 1
	v_cndmask_b32_e32 v181, 0, v181, vcc

; DI unsigned pk2(float a, float b) { f32x2 v = {a, b}; bf16x2_t r = __builtin_convertvector(v, bf16x2_t); return __builtin_bit_cast(unsigned, r); }
; template <int DQK, bool BAND, int QT> ...
;     ...
;         const float mc = -m[qt] * cc;
;         float ls = 0.f;
; #pragma unroll
;         for (int a = 0; a < 2; ++a) {
; #pragma unroll
;           for (int r = 0; r < 16; ++r) { const float pv = __builtin_amdgcn_exp2f(fmaf(s[a][qt][r], cc, mc)); s[a][qt][r] = pv; ls += pv; }
; #pragma unroll
;           for (int s2 = 0; s2 < 2; ++s2) {
;             u32x4 pk;
;             pk.x = pk2(s[a][qt][8 * s2 + 0], s[a][qt][8 * s2 + 1]);
;             pk.y = pk2(s[a][qt][8 * s2 + 2], s[a][qt][8 * s2 + 3]);
;             pk.z = pk2(s[a][qt][8 * s2 + 4], s[a][qt][8 * s2 + 5]);
;             pk.w = pk2(s[a][qt][8 * s2 + 6], s[a][qt][8 * s2 + 7]);
;             pf[qt][a * 2 + s2] = __builtin_bit_cast(bf16x8, pk);
;           }
;         }
;         l[qt] += ls;
.Lmla_nostage:
	v_mul_f32_e32 v254, 0xbe16c740, v237
	v_mul_f32_e32 v255, 0xbe16c740, v238
	v_fmamk_f32 v82, v82, 0x3e16c740, v254
	v_fmamk_f32 v114, v114, 0x3e16c740, v255
	v_fmamk_f32 v83, v83, 0x3e16c740, v254
	v_fmamk_f32 v115, v115, 0x3e16c740, v255
	v_fmamk_f32 v84, v84, 0x3e16c740, v254
	v_fmamk_f32 v116, v116, 0x3e16c740, v255
	v_fmamk_f32 v85, v85, 0x3e16c740, v254
	v_fmamk_f32 v117, v117, 0x3e16c740, v255
	v_fmamk_f32 v86, v86, 0x3e16c740, v254
	v_fmamk_f32 v118, v118, 0x3e16c740, v255
	v_fmamk_f32 v87, v87, 0x3e16c740, v254
	v_fmamk_f32 v119, v119, 0x3e16c740, v255
	v_fmamk_f32 v88, v88, 0x3e16c740, v254
	v_fmamk_f32 v120, v120, 0x3e16c740, v255
	v_fmamk_f32 v89, v89, 0x3e16c740, v254
	v_fmamk_f32 v121, v121, 0x3e16c740, v255
	v_exp_f32_e32 v82, v82
	v_exp_f32_e32 v114, v114
	v_exp_f32_e32 v83, v83
	v_exp_f32_e32 v115, v115
	v_exp_f32_e32 v84, v84
	v_exp_f32_e32 v116, v116
	v_exp_f32_e32 v85, v85
	v_exp_f32_e32 v117, v117
	v_exp_f32_e32 v86, v86
	v_exp_f32_e32 v118, v118
	v_exp_f32_e32 v87, v87
	v_exp_f32_e32 v119, v119
	v_exp_f32_e32 v88, v88
	v_exp_f32_e32 v120, v120
	v_exp_f32_e32 v89, v89
	v_exp_f32_e32 v121, v121
	v_fmamk_f32 v90, v90, 0x3e16c740, v254
	v_fmamk_f32 v122, v122, 0x3e16c740, v255
	v_fmamk_f32 v91, v91, 0x3e16c740, v254
	v_fmamk_f32 v123, v123, 0x3e16c740, v255
	v_fmamk_f32 v92, v92, 0x3e16c740, v254
	v_fmamk_f32 v124, v124, 0x3e16c740, v255
	v_fmamk_f32 v93, v93, 0x3e16c740, v254
	v_fmamk_f32 v125, v125, 0x3e16c740, v255
	v_fmamk_f32 v94, v94, 0x3e16c740, v254
	v_fmamk_f32 v126, v126, 0x3e16c740, v255
	v_fmamk_f32 v95, v95, 0x3e16c740, v254
	v_fmamk_f32 v127, v127, 0x3e16c740, v255
	v_fmamk_f32 v96, v96, 0x3e16c740, v254
	v_fmamk_f32 v128, v128, 0x3e16c740, v255
	v_fmamk_f32 v97, v97, 0x3e16c740, v254
	v_fmamk_f32 v129, v129, 0x3e16c740, v255
	v_exp_f32_e32 v90, v90
	v_exp_f32_e32 v122, v122
	v_mov_b32_e32 v239, v82
	v_mov_b32_e32 v253, v114
	v_exp_f32_e32 v91, v91
	v_exp_f32_e32 v123, v123
	v_add_f32_e32 v239, v239, v83
	v_add_f32_e32 v253, v253, v115
	v_exp_f32_e32 v92, v92
	v_exp_f32_e32 v124, v124
	v_add_f32_e32 v239, v239, v84
	v_add_f32_e32 v253, v253, v116
	v_exp_f32_e32 v93, v93
	v_exp_f32_e32 v125, v125
	v_add_f32_e32 v239, v239, v85
	v_add_f32_e32 v253, v253, v117
	v_exp_f32_e32 v94, v94
	v_exp_f32_e32 v126, v126
	v_add_f32_e32 v239, v239, v86
	v_add_f32_e32 v253, v253, v118
	v_exp_f32_e32 v95, v95
	v_exp_f32_e32 v127, v127
	v_add_f32_e32 v239, v239, v87
	v_add_f32_e32 v253, v253, v119
	v_exp_f32_e32 v96, v96
	v_exp_f32_e32 v128, v128
	v_add_f32_e32 v239, v239, v88
	v_add_f32_e32 v253, v253, v120
	v_exp_f32_e32 v97, v97
	v_exp_f32_e32 v129, v129
	v_add_f32_e32 v239, v239, v89
	v_add_f32_e32 v253, v253, v121
	v_cvt_pk_bf16_f32 v82, v82, v83
	v_cvt_pk_bf16_f32 v114, v114, v115
	v_cvt_pk_bf16_f32 v83, v84, v85
	v_cvt_pk_bf16_f32 v115, v116, v117
	v_cvt_pk_bf16_f32 v84, v86, v87
	v_cvt_pk_bf16_f32 v116, v118, v119
	v_cvt_pk_bf16_f32 v85, v88, v89
	v_cvt_pk_bf16_f32 v117, v120, v121
	v_fmamk_f32 v66, v66, 0x3e16c740, v254
	v_fmamk_f32 v98, v98, 0x3e16c740, v255
	v_fmamk_f32 v67, v67, 0x3e16c740, v254
	v_fmamk_f32 v99, v99, 0x3e16c740, v255
	v_fmamk_f32 v68, v68, 0x3e16c740, v254
	v_fmamk_f32 v100, v100, 0x3e16c740, v255
	v_fmamk_f32 v69, v69, 0x3e16c740, v254
	v_fmamk_f32 v101, v101, 0x3e16c740, v255
	v_fmamk_f32 v70, v70, 0x3e16c740, v254
	v_fmamk_f32 v102, v102, 0x3e16c740, v255
	v_fmamk_f32 v71, v71, 0x3e16c740, v254
	v_fmamk_f32 v103, v103, 0x3e16c740, v255
	v_fmamk_f32 v72, v72, 0x3e16c740, v254
	v_fmamk_f32 v104, v104, 0x3e16c740, v255
	v_fmamk_f32 v73, v73, 0x3e16c740, v254
	v_fmamk_f32 v105, v105, 0x3e16c740, v255
	v_exp_f32_e32 v66, v66
	v_exp_f32_e32 v98, v98
	v_add_f32_e32 v239, v239, v90
	v_add_f32_e32 v253, v253, v122
	v_exp_f32_e32 v67, v67
	v_exp_f32_e32 v99, v99
	v_add_f32_e32 v239, v239, v91
	v_add_f32_e32 v253, v253, v123
	v_exp_f32_e32 v68, v68
	v_exp_f32_e32 v100, v100
	v_add_f32_e32 v239, v239, v92
	v_add_f32_e32 v253, v253, v124
	v_exp_f32_e32 v69, v69
	v_exp_f32_e32 v101, v101
	v_add_f32_e32 v239, v239, v93
	v_add_f32_e32 v253, v253, v125
	v_exp_f32_e32 v70, v70
	v_exp_f32_e32 v102, v102
	v_add_f32_e32 v239, v239, v94
	v_add_f32_e32 v253, v253, v126
	v_exp_f32_e32 v71, v71
	v_exp_f32_e32 v103, v103
	v_add_f32_e32 v239, v239, v95
	v_add_f32_e32 v253, v253, v127
	v_exp_f32_e32 v72, v72
	v_exp_f32_e32 v104, v104
	v_add_f32_e32 v239, v239, v96
	v_add_f32_e32 v253, v253, v128
	v_exp_f32_e32 v73, v73
	v_exp_f32_e32 v105, v105
	v_add_f32_e32 v239, v239, v97
	v_add_f32_e32 v253, v253, v129
	v_cvt_pk_bf16_f32 v90, v90, v91
	v_cvt_pk_bf16_f32 v122, v122, v123
	v_cvt_pk_bf16_f32 v91, v92, v93
	v_cvt_pk_bf16_f32 v123, v124, v125
	v_cvt_pk_bf16_f32 v92, v94, v95
	v_cvt_pk_bf16_f32 v124, v126, v127
	v_cvt_pk_bf16_f32 v93, v96, v97
	v_cvt_pk_bf16_f32 v125, v128, v129
; #define MFMA(a, b, c) __builtin_amdgcn_mfma_f32_32x32x16_bf16((a), (b), (c), 0, 0, 0)
; DI unsigned pk2(float a, float b) { f32x2 v = {a, b}; bf16x2_t r = __builtin_convertvector(v, bf16x2_t); return __builtin_bit_cast(unsigned, r); }
; template <int DQK, bool BAND, int QT> ...
;     ...
;         const float mc = -m[qt] * cc;
;         float ls = 0.f;
; #pragma unroll
;         for (int a = 0; a < 2; ++a) {
; #pragma unroll
;           for (int r = 0; r < 16; ++r) { const float pv = __builtin_amdgcn_exp2f(fmaf(s[a][qt][r], cc, mc)); s[a][qt][r] = pv; ls += pv; }
; #pragma unroll
;           for (int s2 = 0; s2 < 2; ++s2) {
;             u32x4 pk;
;             pk.x = pk2(s[a][qt][8 * s2 + 0], s[a][qt][8 * s2 + 1]);
;             pk.y = pk2(s[a][qt][8 * s2 + 2], s[a][qt][8 * s2 + 3]);
;             pk.z = pk2(s[a][qt][8 * s2 + 4], s[a][qt][8 * s2 + 5]);
;             pk.w = pk2(s[a][qt][8 * s2 + 6], s[a][qt][8 * s2 + 7]);
;             pf[qt][a * 2 + s2] = __builtin_bit_cast(bf16x8, pk);
;           }
;         }
;         l[qt] += ls;
;       }
;       __builtin_amdgcn_s_setprio(0);
;       if (more) lstore(lds + ((it + 1) & 1) * ST);
; #pragma unroll
;       for (int ks = 0; ks < 4; ++ks) {
;         const bf16x8 v0 = *(const bf16x8*)(st + v_rd + ks * 32);
;         const bf16x8 v1 = *(const bf16x8*)(st + v_rd + 32 * LROW + ks * 32);
; #pragma unroll
;         for (int qt = 0; qt < QT; ++qt) {
;           o[0][qt] = MFMA(v0, pf[qt][ks], o[0][qt]);
;           o[1][qt] = MFMA(v1, pf[qt][ks], o[1][qt]);
;         }
;       }
;     } else {
;       if (more) lstore(lds + ((it + 1) & 1) * ST);
;     }
;     __syncthreads();
	v_fmamk_f32 v74, v74, 0x3e16c740, v254
	v_fmamk_f32 v106, v106, 0x3e16c740, v255
	v_fmamk_f32 v75, v75, 0x3e16c740, v254
	v_fmamk_f32 v107, v107, 0x3e16c740, v255
	v_fmamk_f32 v76, v76, 0x3e16c740, v254
	v_fmamk_f32 v108, v108, 0x3e16c740, v255
	v_fmamk_f32 v77, v77, 0x3e16c740, v254
	v_fmamk_f32 v109, v109, 0x3e16c740, v255
	v_fmamk_f32 v78, v78, 0x3e16c740, v254
	v_fmamk_f32 v110, v110, 0x3e16c740, v255
	v_fmamk_f32 v79, v79, 0x3e16c740, v254
	v_fmamk_f32 v111, v111, 0x3e16c740, v255
	v_fmamk_f32 v80, v80, 0x3e16c740, v254
	v_fmamk_f32 v112, v112, 0x3e16c740, v255
	v_fmamk_f32 v81, v81, 0x3e16c740, v254
	v_fmamk_f32 v113, v113, 0x3e16c740, v255
	v_exp_f32_e32 v74, v74
	v_exp_f32_e32 v106, v106
	v_add_f32_e32 v239, v239, v66
	v_add_f32_e32 v253, v253, v98
	v_exp_f32_e32 v75, v75
	v_exp_f32_e32 v107, v107
	v_add_f32_e32 v239, v239, v67
	v_add_f32_e32 v253, v253, v99
	v_exp_f32_e32 v76, v76
	v_exp_f32_e32 v108, v108
	v_add_f32_e32 v239, v239, v68
	v_add_f32_e32 v253, v253, v100
	v_exp_f32_e32 v77, v77
	v_exp_f32_e32 v109, v109
	v_add_f32_e32 v239, v239, v69
	v_add_f32_e32 v253, v253, v101
	v_exp_f32_e32 v78, v78
	v_exp_f32_e32 v110, v110
	v_add_f32_e32 v239, v239, v70
	v_add_f32_e32 v253, v253, v102
	v_exp_f32_e32 v79, v79
	v_exp_f32_e32 v111, v111
	v_add_f32_e32 v239, v239, v71
	v_add_f32_e32 v253, v253, v103
	v_exp_f32_e32 v80, v80
	v_exp_f32_e32 v112, v112
	v_add_f32_e32 v239, v239, v72
	v_add_f32_e32 v253, v253, v104
	v_exp_f32_e32 v81, v81
	v_exp_f32_e32 v113, v113
	v_add_f32_e32 v239, v239, v73
	v_add_f32_e32 v253, v253, v105
	v_cvt_pk_bf16_f32 v66, v66, v67
	v_cvt_pk_bf16_f32 v98, v98, v99
	v_cvt_pk_bf16_f32 v67, v68, v69
	v_cvt_pk_bf16_f32 v99, v100, v101
	v_cvt_pk_bf16_f32 v68, v70, v71
	v_cvt_pk_bf16_f32 v100, v102, v103
	v_cvt_pk_bf16_f32 v69, v72, v73
	v_cvt_pk_bf16_f32 v101, v104, v105
	v_add_f32_e32 v239, v239, v74
	v_add_f32_e32 v253, v253, v106
	v_add_f32_e32 v239, v239, v75
	v_add_f32_e32 v253, v253, v107
	v_add_f32_e32 v239, v239, v76
	v_add_f32_e32 v253, v253, v108
	v_add_f32_e32 v239, v239, v77
	v_add_f32_e32 v253, v253, v109
	v_add_f32_e32 v239, v239, v78
	v_add_f32_e32 v253, v253, v110
	v_add_f32_e32 v239, v239, v79
	v_add_f32_e32 v253, v253, v111
	v_add_f32_e32 v239, v239, v80
	v_add_f32_e32 v253, v253, v112
	v_add_f32_e32 v239, v239, v81
	v_add_f32_e32 v253, v253, v113
	v_cvt_pk_bf16_f32 v74, v74, v75
	v_cvt_pk_bf16_f32 v106, v106, v107
	v_cvt_pk_bf16_f32 v75, v76, v77
	v_cvt_pk_bf16_f32 v107, v108, v109
	v_cvt_pk_bf16_f32 v76, v78, v79
	v_cvt_pk_bf16_f32 v108, v110, v111
	v_cvt_pk_bf16_f32 v77, v80, v81
	v_cvt_pk_bf16_f32 v109, v112, v113
	v_add_f32_e32 v236, v236, v239
	v_add_f32_e32 v207, v207, v253
	s_setprio 2
	ds_read_b128 v[86:89], v234 offset:13312
	ds_read_b128 v[94:97], v234 offset:17920
	ds_read_b128 v[70:73], v234 offset:13344
	ds_read_b128 v[78:81], v234 offset:17952
	ds_read_b128 v[118:121], v234 offset:13376
	ds_read_b128 v[126:129], v234 offset:17984
	ds_read_b128 v[102:105], v234 offset:13408
	ds_read_b128 v[110:113], v234 offset:18016
	s_waitcnt lgkmcnt(7)
	v_mfma_f32_32x32x16_bf16 v[50:65], v[86:89], v[82:85], v[50:65]
	v_mfma_f32_32x32x16_bf16 v[18:33], v[86:89], v[114:117], v[18:33]
	s_waitcnt lgkmcnt(6)
	v_mfma_f32_32x32x16_bf16 v[34:49], v[94:97], v[82:85], v[34:49]
	v_mfma_f32_32x32x16_bf16 v[2:17], v[94:97], v[114:117], v[2:17]
	v_lshl_add_u64 v[208:209], v[208:209], 0, s[76:77]
	v_lshl_add_u64 v[210:211], v[210:211], 0, s[76:77]
	v_lshl_add_u64 v[212:213], v[212:213], 0, s[84:85]
	v_lshl_add_u64 v[214:215], v[214:215], 0, s[84:85]
	v_lshl_add_u64 v[216:217], v[216:217], 0, s[84:85]
	s_waitcnt lgkmcnt(5)
	v_mfma_f32_32x32x16_bf16 v[50:65], v[70:73], v[90:93], v[50:65]
	v_mfma_f32_32x32x16_bf16 v[18:33], v[70:73], v[122:125], v[18:33]
	s_waitcnt lgkmcnt(4)
	v_mfma_f32_32x32x16_bf16 v[34:49], v[78:81], v[90:93], v[34:49]
	v_mfma_f32_32x32x16_bf16 v[2:17], v[78:81], v[122:125], v[2:17]
	s_waitcnt lgkmcnt(3)
	v_mfma_f32_32x32x16_bf16 v[50:65], v[118:121], v[66:69], v[50:65]
	v_mfma_f32_32x32x16_bf16 v[18:33], v[118:121], v[98:101], v[18:33]
	s_waitcnt lgkmcnt(2)
	v_mfma_f32_32x32x16_bf16 v[34:49], v[126:129], v[66:69], v[34:49]
	v_mfma_f32_32x32x16_bf16 v[2:17], v[126:129], v[98:101], v[2:17]
	s_bitcmp1_b32 s1, 0
	s_cselect_b32 s7, -1, 1
	s_mulk_i32 s7, 0x5800
	v_add_u32_e32 v235, s7, v235
	v_add_u32_e32 v234, s7, v234
	s_add_i32 s1, s1, 1
	s_add_i32 s6, s6, 64
	s_waitcnt lgkmcnt(0)
	s_barrier
	v_mfma_f32_32x32x16_bf16 v[50:65], v[102:105], v[74:77], v[50:65]
	v_mfma_f32_32x32x16_bf16 v[18:33], v[102:105], v[106:109], v[18:33]
	v_mfma_f32_32x32x16_bf16 v[34:49], v[110:113], v[74:77], v[34:49]
	v_mfma_f32_32x32x16_bf16 v[2:17], v[110:113], v[106:109], v[2:17]
	s_cmp_lg_u32 s21, s1
	s_cbranch_scc1 .Lmla_top
	s_setprio 0
	s_branch .LBB0_663
